# grid barrier: all workgroups wait on the TOP arrival counter (>= (gen+1)*nXCD) instead of a generation word bumped after the last leader's atomic returned
# speedup vs baseline: 1.0088x; 1.0088x over previous
.LBB0_38:
	s_or_b64 exec, exec, s[20:21]
	v_cvt_f32_u32_e32 v4, v2
	s_waitcnt vmcnt(0)
	v_readfirstlane_b32 s2, v3
	v_sub_u32_e32 v3, 0, v2
	v_rcp_iflag_f32_e32 v4, v4
	v_add_u32_e32 v5, s2, v1
	v_mul_f32_e32 v4, 0x4f7ffffe, v4
	v_cvt_u32_f32_e32 v4, v4
	v_mul_lo_u32 v1, v3, v4
	v_mul_hi_u32 v1, v4, v1
	v_add_u32_e32 v1, v4, v1
	v_mul_hi_u32 v1, v5, v1
	v_mul_lo_u32 v3, v1, v2
	v_sub_u32_e32 v3, v5, v3
	v_add_u32_e32 v4, 1, v1
	v_sub_u32_e32 v6, v3, v2
	v_cmp_ge_u32_e32 vcc, v3, v2
	s_nop 1
	v_cndmask_b32_e32 v1, v1, v4, vcc
	v_cndmask_b32_e32 v3, v3, v6, vcc
	v_add_u32_e32 v4, 1, v1
	v_cmp_ge_u32_e32 vcc, v3, v2
	v_add_u32_e32 v3, 1, v5
	s_nop 0
	v_cndmask_b32_e32 v1, v1, v4, vcc
	v_mul_lo_u32 v4, v2, v1
	v_add_u32_e32 v2, v4, v2
	v_cmp_ne_u32_e32 vcc, v3, v2
	s_and_saveexec_b64 s[20:21], vcc
	s_xor_b64 s[20:21], exec, s[20:21]
	s_cbranch_execz .LBB0_52
	v_readlane_b32 s22, v215, 16
	v_readlane_b32 s23, v215, 17
	s_waitcnt lgkmcnt(0)
	v_add_u32_e32 v1, 1, v1
	v_mul_lo_u32 v1, v1, v0
	s_nop 3
	global_load_dword v0, v65, s[22:23] sc1
	s_waitcnt vmcnt(0)
	v_cmp_lt_u32_e32 vcc, v0, v1
	s_and_saveexec_b64 s[28:29], vcc
	s_cbranch_execz .LBB0_51
	s_mov_b32 s2, 1
	s_mov_b64 s[34:35], 0
	s_branch .LBB0_42

.LBB0_44:
	v_readlane_b32 s22, v215, 16
	v_readlane_b32 s23, v215, 17
	s_add_i32 s2, s2, 1
	s_mov_b64 s[40:41], -1
	s_nop 2
	global_load_dword v0, v65, s[22:23] sc1
	s_waitcnt vmcnt(0)
	v_cmp_ge_u32_e32 vcc, v0, v1
	s_orn2_b64 s[38:39], vcc, exec
	s_branch .LBB0_41

.LBB0_55:
	s_or_b64 exec, exec, s[28:29]
	v_cvt_f32_u32_e32 v3, v0
	s_waitcnt vmcnt(0)
	v_readfirstlane_b32 s2, v2
	v_sub_u32_e32 v2, 0, v0
	v_readlane_b32 s20, v215, 18
	v_rcp_iflag_f32_e32 v3, v3
	v_add_u32_e32 v1, s2, v1
	v_add_u32_e32 v4, 1, v1
	v_readlane_b32 s21, v215, 19
	v_mul_f32_e32 v3, 0x4f7ffffe, v3
	v_cvt_u32_f32_e32 v3, v3
	s_mov_b64 s[28:29], -1
	v_mul_lo_u32 v2, v2, v3
	v_mul_hi_u32 v2, v3, v2
	v_add_u32_e32 v2, v3, v2
	v_mul_hi_u32 v2, v1, v2
	v_mul_lo_u32 v3, v2, v0
	v_sub_u32_e32 v1, v1, v3
	v_add_u32_e32 v5, 1, v2
	v_sub_u32_e32 v3, v1, v0
	v_cmp_ge_u32_e32 vcc, v1, v0
	s_nop 1
	v_cndmask_b32_e32 v2, v2, v5, vcc
	v_cndmask_b32_e32 v1, v1, v3, vcc
	v_add_u32_e32 v3, 1, v2
	v_cmp_ge_u32_e32 vcc, v1, v0
	s_nop 1
	v_cndmask_b32_e32 v2, v2, v3, vcc
	v_mul_lo_u32 v1, v0, v2
	v_add_u32_e32 v0, v1, v0
	v_mov_b32_e32 v5, v0
	v_cmp_ne_u32_e32 vcc, v4, v0
	v_mov_b64_e32 v[0:1], s[20:21]
	s_and_saveexec_b64 s[20:21], vcc
	s_cbranch_execz .LBB0_67
	v_readlane_b32 s22, v215, 16
	v_readlane_b32 s23, v215, 17
	s_mov_b64 s[34:35], 0
	s_nop 3
	global_load_dword v0, v65, s[22:23] sc1
	s_waitcnt vmcnt(0)
	v_cmp_lt_u32_e32 vcc, v0, v5
	s_and_saveexec_b64 s[28:29], vcc
	s_cbranch_execz .LBB0_66
	s_mov_b32 s2, 1
	s_branch .LBB0_59

.LBB0_61:
	v_readlane_b32 s22, v215, 16
	v_readlane_b32 s23, v215, 17
	s_add_i32 s2, s2, 1
	s_mov_b64 s[40:41], -1
	s_nop 2
	global_load_dword v0, v65, s[22:23] sc1
	s_waitcnt vmcnt(0)
	v_cmp_ge_u32_e32 vcc, v0, v5
	s_orn2_b64 s[38:39], vcc, exec
	s_branch .LBB0_58
